# FoX unmasked tile path: removed 48 loop-carried v_mov_b64 accumulator copies per tile (o stays in v[64:95]; copies only on loop exit)
# speedup vs baseline: 1.0160x; 1.0160x over previous
.LBB0_391:
	s_and_b64 vcc, exec, s[10:11]
	s_cbranch_vccz .LBB0_393
	ds_read_b128 v[2:5], v0 offset:96
	ds_read_b128 v[6:9], v0 offset:64
	ds_read_b128 v[10:13], v0
	ds_read_b128 v[32:35], v0 offset:32
	ds_read_b128 v[36:39], v0 offset:224
	ds_read_b128 v[40:43], v0 offset:192
	ds_read_b128 v[112:115], v0 offset:160
	ds_read_b128 v[116:119], v0 offset:128
	s_waitcnt lgkmcnt(4)
	v_add3_u32 v234, s86, v229, v227
	v_sub_f32_e32 v111, v63, v5
	v_sub_f32_e32 v110, v62, v4
	v_sub_f32_e32 v109, v61, v3
	v_sub_f32_e32 v108, v60, v2
	v_sub_f32_e32 v107, v59, v9
	v_sub_f32_e32 v106, v58, v8
	v_sub_f32_e32 v105, v57, v7
	v_sub_f32_e32 v104, v56, v6
	v_sub_f32_e32 v103, v55, v35
	v_sub_f32_e32 v102, v54, v34
	v_sub_f32_e32 v101, v53, v33
	v_sub_f32_e32 v100, v52, v32
	v_sub_f32_e32 v99, v51, v13
	v_sub_f32_e32 v98, v50, v12
	v_sub_f32_e32 v97, v49, v11
	v_sub_f32_e32 v96, v48, v10
	s_waitcnt lgkmcnt(0)
	ds_read_b128 v[2:5], v234 offset:96
	ds_read_b128 v[6:9], v234 offset:64
	ds_read_b128 v[10:13], v234
	ds_read_b128 v[120:123], v234 offset:32
	ds_read_b128 v[124:127], v234 offset:4704
	ds_read_b128 v[128:131], v234 offset:4672
	ds_read_b128 v[132:135], v234 offset:4640
	ds_read_b128 v[136:139], v234 offset:4608
	s_waitcnt lgkmcnt(4)
	v_sub_f32_e32 v47, v63, v39
	v_mfma_f32_32x32x16_bf16 v[96:111], v[10:13], v[144:147], v[96:111]
	v_sub_f32_e32 v46, v62, v38
	v_sub_f32_e32 v45, v61, v37
	v_sub_f32_e32 v44, v60, v36
	v_sub_f32_e32 v43, v59, v43
	v_sub_f32_e32 v42, v58, v42
	v_sub_f32_e32 v41, v57, v41
	v_sub_f32_e32 v40, v56, v40
	v_sub_f32_e32 v39, v55, v115
	v_sub_f32_e32 v38, v54, v114
	v_sub_f32_e32 v37, v53, v113
	v_sub_f32_e32 v36, v52, v112
	v_sub_f32_e32 v35, v51, v119
	v_sub_f32_e32 v34, v50, v118
	v_sub_f32_e32 v33, v49, v117
	v_sub_f32_e32 v32, v48, v116
	s_waitcnt lgkmcnt(0)
	v_mfma_f32_32x32x16_bf16 v[96:111], v[120:123], v[148:151], v[96:111]
	v_mfma_f32_32x32x16_bf16 v[32:47], v[136:139], v[144:147], v[32:47]
	v_mfma_f32_32x32x16_bf16 v[32:47], v[132:135], v[148:151], v[32:47]
	v_mfma_f32_32x32x16_bf16 v[96:111], v[6:9], v[152:155], v[96:111]
	v_mfma_f32_32x32x16_bf16 v[32:47], v[128:131], v[152:155], v[32:47]
	v_mfma_f32_32x32x16_bf16 v[96:111], v[2:5], v[156:159], v[96:111]
	v_add3_u32 v4, s77, v230, v211
	ds_read_b64_tr_b16 v[6:7], v4 offset:36864
	ds_read_b64_tr_b16 v[8:9], v4 offset:38400
	ds_read_b64_tr_b16 v[12:13], v4 offset:38464
	ds_read_b64_tr_b16 v[10:11], v4 offset:36928
	ds_read_b64_tr_b16 v[112:113], v4 offset:39936
	ds_read_b64_tr_b16 v[114:115], v4 offset:41472
	ds_read_b64_tr_b16 v[118:119], v4 offset:41536
	ds_read_b64_tr_b16 v[116:117], v4 offset:40000
	v_mfma_f32_32x32x16_bf16 v[32:47], v[124:127], v[156:159], v[32:47]
	s_nop 1
	v_exp_f32_e32 v2, v96
	v_exp_f32_e32 v15, v97
	v_exp_f32_e32 v121, v98
	v_exp_f32_e32 v123, v99
	v_exp_f32_e32 v125, v100
	v_exp_f32_e32 v127, v101
	v_exp_f32_e32 v129, v102
	v_exp_f32_e32 v131, v103
	v_exp_f32_e32 v133, v104
	v_exp_f32_e32 v135, v105
	v_exp_f32_e32 v137, v106
	v_exp_f32_e32 v139, v107
	v_exp_f32_e32 v141, v108
	v_exp_f32_e32 v109, v109
	v_exp_f32_e32 v143, v110
	v_exp_f32_e32 v111, v111
	v_cvt_pk_bf16_f32 v96, v2, v15
	v_cvt_pk_bf16_f32 v97, v121, v123
	v_cvt_pk_bf16_f32 v98, v125, v127
	v_cvt_pk_bf16_f32 v99, v129, v131
	v_cvt_pk_bf16_f32 v100, v133, v135
	v_cvt_pk_bf16_f32 v101, v137, v139
	v_cvt_pk_bf16_f32 v102, v141, v109
	v_cvt_pk_bf16_f32 v103, v143, v111
	s_waitcnt lgkmcnt(0)
	v_add_f32_e32 v3, 0, v2
	v_mfma_f32_32x32x16_bf16 v[64:79], v[6:9], v[96:99], v[64:79]
	v_mfma_f32_32x32x16_bf16 v[80:95], v[10:13], v[96:99], v[80:95]
	ds_read_b64_tr_b16 v[6:7], v4 offset:43008
	ds_read_b64_tr_b16 v[8:9], v4 offset:44544
	ds_read_b64_tr_b16 v[12:13], v4 offset:44608
	ds_read_b64_tr_b16 v[10:11], v4 offset:43072
	ds_read_b64_tr_b16 v[96:97], v4 offset:46080
	ds_read_b64_tr_b16 v[98:99], v4 offset:47616
	ds_read_b64_tr_b16 v[106:107], v4 offset:47680
	ds_read_b64_tr_b16 v[104:105], v4 offset:46144
	v_mfma_f32_32x32x16_bf16 v[64:79], v[112:115], v[100:103], v[64:79]
	v_mfma_f32_32x32x16_bf16 v[80:95], v[116:119], v[100:103], v[80:95]
	v_exp_f32_e32 v14, v32
	v_exp_f32_e32 v120, v33
	v_exp_f32_e32 v122, v34
	v_exp_f32_e32 v124, v35
	v_mov_b32_e32 v2, v1
	v_add_f32_e32 v2, v14, v2
	v_add_f32_e32 v3, v15, v3
	v_exp_f32_e32 v126, v36
	v_add_f32_e32 v2, v120, v2
	v_add_f32_e32 v3, v121, v3
	v_exp_f32_e32 v128, v37
	v_add_f32_e32 v2, v122, v2
	v_add_f32_e32 v3, v123, v3
	v_exp_f32_e32 v130, v38
	v_add_f32_e32 v2, v124, v2
	v_add_f32_e32 v3, v125, v3
	v_exp_f32_e32 v132, v39
	v_exp_f32_e32 v134, v40
	v_add_f32_e32 v2, v126, v2
	v_add_f32_e32 v3, v127, v3
	v_exp_f32_e32 v136, v41
	v_add_f32_e32 v2, v128, v2
	v_add_f32_e32 v3, v129, v3
	v_exp_f32_e32 v138, v42
	v_exp_f32_e32 v140, v43
	v_exp_f32_e32 v108, v44
	v_exp_f32_e32 v142, v45
	v_exp_f32_e32 v110, v46
	v_exp_f32_e32 v192, v47
	v_add_f32_e32 v2, v130, v2
	v_add_f32_e32 v3, v131, v3
	v_cvt_pk_bf16_f32 v32, v14, v120
	v_cvt_pk_bf16_f32 v33, v122, v124
	v_cvt_pk_bf16_f32 v34, v126, v128
	v_cvt_pk_bf16_f32 v35, v130, v132
	v_cvt_pk_bf16_f32 v36, v134, v136
	v_cvt_pk_bf16_f32 v37, v138, v140
	v_cvt_pk_bf16_f32 v38, v108, v142
	v_cvt_pk_bf16_f32 v39, v110, v192
	s_waitcnt lgkmcnt(0)
	v_add_f32_e32 v2, v132, v2
	v_add_f32_e32 v3, v133, v3
	v_mfma_f32_32x32x16_bf16 v[64:79], v[6:9], v[32:35], v[64:79]
	v_add_f32_e64 v2, v134, v2
	v_add_f32_e64 v3, v135, v3
	v_add_f32_e64 v2, v136, v2
	v_add_f32_e64 v3, v137, v3
	v_add_f32_e64 v2, v138, v2
	v_add_f32_e64 v3, v139, v3
	v_add_f32_e32 v2, v140, v2
	v_add_f32_e32 v3, v141, v3
	v_mfma_f32_32x32x16_bf16 v[80:95], v[10:13], v[32:35], v[80:95]
	v_add_f32_e64 v2, v108, v2
	v_add_f32_e64 v3, v109, v3
	v_add_f32_e64 v2, v142, v2
	v_add_f32_e64 v3, v143, v3
	v_add_f32_e64 v2, v110, v2
	v_add_f32_e64 v3, v111, v3
	v_add_f32_e32 v2, v192, v2
	v_add_f32_e32 v3, v193, v3
	v_mfma_f32_32x32x16_bf16 v[64:79], v[96:99], v[36:39], v[64:79]
	v_pk_add_f32 v[2:3], v[2:3], v[2:3] op_sel_hi:[0,1]
	v_mfma_f32_32x32x16_bf16 v[80:95], v[104:107], v[36:39], v[80:95]
	ds_read_b128 v[6:9], v0 offset:352
	ds_read_b128 v[10:13], v0 offset:320
	ds_read_b128 v[96:99], v0 offset:256
	ds_read_b128 v[100:103], v0 offset:288
	ds_read_b128 v[32:35], v0 offset:480
	ds_read_b128 v[36:39], v0 offset:448
	ds_read_b128 v[104:107], v0 offset:416
	ds_read_b128 v[108:111], v0 offset:384
	s_waitcnt lgkmcnt(4)
	s_waitcnt lgkmcnt(0)
	ds_read_b128 v[112:115], v234 offset:9312
	ds_read_b128 v[116:119], v234 offset:9280
	ds_read_b128 v[120:123], v234 offset:9216
	ds_read_b128 v[124:127], v234 offset:9248
	ds_read_b128 v[128:131], v234 offset:13920
	ds_read_b128 v[132:135], v234 offset:13888
	ds_read_b128 v[136:139], v234 offset:13856
	ds_read_b128 v[140:143], v234 offset:13824
	v_sub_f32_e32 v47, v31, v35
	v_sub_f32_e32 v46, v30, v34
	v_sub_f32_e32 v45, v29, v33
	v_sub_f32_e32 v44, v28, v32
	v_sub_f32_e32 v43, v27, v39
	v_sub_f32_e32 v42, v26, v38
	v_sub_f32_e32 v41, v25, v37
	v_sub_f32_e32 v40, v24, v36
	v_sub_f32_e32 v39, v23, v107
	v_sub_f32_e32 v38, v22, v106
	v_sub_f32_e32 v37, v21, v105
	v_sub_f32_e32 v36, v20, v104
	v_sub_f32_e32 v35, v19, v111
	v_sub_f32_e32 v34, v18, v110
	v_sub_f32_e32 v33, v17, v109
	v_sub_f32_e32 v32, v16, v108
	v_sub_f32_e32 v111, v63, v9
	v_sub_f32_e32 v110, v62, v8
	v_sub_f32_e32 v109, v61, v7
	v_sub_f32_e32 v108, v60, v6
	v_sub_f32_e32 v107, v59, v13
	v_sub_f32_e32 v106, v58, v12
	v_sub_f32_e32 v105, v57, v11
	v_sub_f32_e32 v104, v56, v10
	v_sub_f32_e32 v103, v55, v103
	v_sub_f32_e32 v102, v54, v102
	v_sub_f32_e32 v101, v53, v101
	v_sub_f32_e32 v100, v52, v100
	v_sub_f32_e32 v99, v51, v99
	v_sub_f32_e32 v98, v50, v98
	v_sub_f32_e32 v97, v49, v97
	v_sub_f32_e32 v96, v48, v96
	s_waitcnt lgkmcnt(4)
	s_waitcnt lgkmcnt(0)
	s_nop 0
	v_mfma_f32_32x32x16_bf16 v[32:47], v[140:143], v[144:147], v[32:47]
	v_mfma_f32_32x32x16_bf16 v[96:111], v[120:123], v[144:147], v[96:111]
	v_mfma_f32_32x32x16_bf16 v[96:111], v[124:127], v[148:151], v[96:111]
	v_mfma_f32_32x32x16_bf16 v[32:47], v[136:139], v[148:151], v[32:47]
	v_mfma_f32_32x32x16_bf16 v[96:111], v[116:119], v[152:155], v[96:111]
	v_mfma_f32_32x32x16_bf16 v[32:47], v[132:135], v[152:155], v[32:47]
	v_mfma_f32_32x32x16_bf16 v[96:111], v[112:115], v[156:159], v[96:111]
	ds_read_b64_tr_b16 v[6:7], v4 offset:49152
	ds_read_b64_tr_b16 v[8:9], v4 offset:50688
	ds_read_b64_tr_b16 v[10:11], v4 offset:52224
	ds_read_b64_tr_b16 v[12:13], v4 offset:53760
	ds_read_b64_tr_b16 v[112:113], v4 offset:49216
	ds_read_b64_tr_b16 v[114:115], v4 offset:50752
	ds_read_b64_tr_b16 v[116:117], v4 offset:52288
	ds_read_b64_tr_b16 v[118:119], v4 offset:53824
	v_mfma_f32_32x32x16_bf16 v[32:47], v[128:131], v[156:159], v[32:47]
	s_nop 2
	v_exp_f32_e32 v0, v96
	v_exp_f32_e32 v5, v97
	v_exp_f32_e32 v15, v98
	v_exp_f32_e32 v121, v99
	v_exp_f32_e32 v123, v100
	v_exp_f32_e32 v125, v101
	v_exp_f32_e32 v127, v102
	v_exp_f32_e32 v129, v103
	v_exp_f32_e32 v131, v104
	v_exp_f32_e32 v133, v105
	v_exp_f32_e32 v135, v106
	v_exp_f32_e32 v137, v107
	v_exp_f32_e32 v139, v108
	v_exp_f32_e32 v109, v109
	v_exp_f32_e32 v141, v110
	v_exp_f32_e32 v111, v111
	v_cvt_pk_bf16_f32 v96, v0, v5
	v_cvt_pk_bf16_f32 v97, v15, v121
	v_cvt_pk_bf16_f32 v98, v123, v125
	v_cvt_pk_bf16_f32 v99, v127, v129
	v_cvt_pk_bf16_f32 v100, v131, v133
	v_cvt_pk_bf16_f32 v101, v135, v137
	v_cvt_pk_bf16_f32 v102, v139, v109
	v_cvt_pk_bf16_f32 v103, v141, v111
	s_waitcnt lgkmcnt(0)
	v_add_f32_e32 v143, 0, v0
	v_mfma_f32_32x32x16_bf16 v[64:79], v[6:9], v[96:99], v[64:79]
	v_mfma_f32_32x32x16_bf16 v[64:79], v[10:13], v[100:103], v[64:79]
	v_mfma_f32_32x32x16_bf16 v[80:95], v[112:115], v[96:99], v[80:95]
	ds_read_b64_tr_b16 v[6:7], v4 offset:55296
	ds_read_b64_tr_b16 v[8:9], v4 offset:56832
	ds_read_b64_tr_b16 v[12:13], v4 offset:56896
	ds_read_b64_tr_b16 v[10:11], v4 offset:55360
	ds_read_b64_tr_b16 v[96:97], v4 offset:58368
	ds_read_b64_tr_b16 v[98:99], v4 offset:59904
	ds_read_b64_tr_b16 v[106:107], v4 offset:59968
	ds_read_b64_tr_b16 v[104:105], v4 offset:58432
	v_mfma_f32_32x32x16_bf16 v[80:95], v[116:119], v[100:103], v[80:95]
	v_exp_f32_e32 v4, v32
	v_exp_f32_e32 v14, v33
	v_exp_f32_e32 v120, v34
	v_exp_f32_e32 v122, v35
	v_exp_f32_e32 v124, v36
	v_exp_f32_e32 v126, v37
	v_exp_f32_e32 v128, v38
	v_exp_f32_e32 v130, v39
	v_exp_f32_e32 v132, v40
	v_exp_f32_e32 v134, v41
	v_exp_f32_e32 v136, v42
	v_exp_f32_e32 v138, v43
	v_exp_f32_e32 v108, v44
	v_exp_f32_e32 v140, v45
	v_exp_f32_e32 v110, v46
	v_exp_f32_e32 v2, v47
	v_cvt_pk_bf16_f32 v32, v4, v14
	v_cvt_pk_bf16_f32 v33, v120, v122
	v_cvt_pk_bf16_f32 v34, v124, v126
	v_cvt_pk_bf16_f32 v35, v128, v130
	v_cvt_pk_bf16_f32 v36, v132, v134
	v_cvt_pk_bf16_f32 v37, v136, v138
	v_cvt_pk_bf16_f32 v38, v108, v140
	v_cvt_pk_bf16_f32 v39, v110, v2
	s_waitcnt lgkmcnt(0)
	v_mov_b32_e32 v142, v1
	v_mfma_f32_32x32x16_bf16 v[64:79], v[6:9], v[32:35], v[64:79]
	v_add_f32_e64 v4, v4, v142
	v_add_f32_e64 v5, v5, v143
	v_add_f32_e64 v4, v14, v4
	v_add_f32_e64 v5, v15, v5
	v_add_f32_e64 v4, v120, v4
	v_add_f32_e64 v5, v121, v5
	v_add_f32_e32 v4, v122, v4
	v_add_f32_e32 v5, v123, v5
	v_mfma_f32_32x32x16_bf16 v[80:95], v[10:13], v[32:35], v[80:95]
	v_add_f32_e64 v4, v124, v4
	v_add_f32_e64 v5, v125, v5
	v_add_f32_e64 v4, v126, v4
	v_add_f32_e64 v5, v127, v5
	v_add_f32_e64 v4, v128, v4
	v_add_f32_e64 v5, v129, v5
	v_add_f32_e32 v4, v130, v4
	v_add_f32_e32 v5, v131, v5
	v_mfma_f32_32x32x16_bf16 v[64:79], v[96:99], v[36:39], v[64:79]
	v_add_f32_e64 v4, v132, v4
	v_add_f32_e64 v5, v133, v5
	v_add_f32_e64 v4, v134, v4
	v_add_f32_e64 v5, v135, v5
	v_add_f32_e64 v4, v136, v4
	v_add_f32_e64 v5, v137, v5
	v_mfma_f32_32x32x16_bf16 v[80:95], v[104:107], v[36:39], v[80:95]
	v_add_f32_e64 v4, v138, v4
	v_add_f32_e64 v5, v139, v5
	v_add_f32_e64 v4, v108, v4
	v_add_f32_e64 v5, v109, v5
	v_add_f32_e32 v4, v140, v4
	v_add_f32_e32 v5, v141, v5
	v_add_f32_e32 v4, v110, v4
	v_add_f32_e32 v5, v111, v5
	v_add_f32_e32 v2, v2, v4
	v_add_f32_e32 v3, v3, v5
	v_add_f32_e32 v192, v2, v3
	s_add_i32 s53, s53, 1
	s_add_i32 s14, s14, 4
	s_addk_i32 s76, 0x80
	s_add_i32 s10, s51, s53
	v_add_u32_e32 v251, 0xffffff80, v251
	s_cmp_ge_i32 s10, s26
	v_add_u32_e32 v190, 0x400, v190
	s_cbranch_scc1 .Lfox_exit_cp
	v_mov_b32_e32 v193, v192
	s_branch .LBB0_367
.Lfox_exit_cp:
	s_nop 7
	s_nop 7
	v_mov_b64_e32 v[96:97], v[64:65]
	v_mov_b64_e32 v[98:99], v[66:67]
	v_mov_b64_e32 v[100:101], v[68:69]
	v_mov_b64_e32 v[102:103], v[70:71]
	v_mov_b64_e32 v[104:105], v[72:73]
	v_mov_b64_e32 v[106:107], v[74:75]
	v_mov_b64_e32 v[108:109], v[76:77]
	v_mov_b64_e32 v[110:111], v[78:79]
	v_mov_b64_e32 v[32:33], v[80:81]
	v_mov_b64_e32 v[34:35], v[82:83]
	v_mov_b64_e32 v[36:37], v[84:85]
	v_mov_b64_e32 v[38:39], v[86:87]
	v_mov_b64_e32 v[40:41], v[88:89]
	v_mov_b64_e32 v[42:43], v[90:91]
	v_mov_b64_e32 v[44:45], v[92:93]
	v_mov_b64_e32 v[46:47], v[94:95]
	s_branch .LBB0_396
